# v24 + w_o epilogue: 112 dead v_readlane SGPR restores removed (only s[48:49] of the restored block is used)
# baseline (speedup 1.0000x reference)
; __device__ __forceinline__ unsigned pk2(float a, float b) { f32x2_t v = {a, b}; bf16x2v_t r = __builtin_convertvector(v, bf16x2v_t); return __builtin_bit_cast(unsigned, r); }
;     __device__ __forceinline__ void operator()(const f32x4 (&acc)[2][2][4][2], const Unit& u, int wr, int wc, int fr, int fq) const {
;         const int row0 = u.pm * BM + wr * 64 + fr; const int col0 = u.pn * BM + wc * 32 + 8 * fq;
; #pragma unroll
;         for (int ai = 0; ai < 2; ++ai)
; #pragma unroll
;             for (int m = 0; m < 4; ++m) { const int row = row0 + ai * HALF + m * 16; const size_t off = (size_t)row * ldc + col0; float s = 0.f;
; #pragma unroll
;                 for (int bj = 0; bj < 2; ++bj) { const size_t o2 = off + bj * HALF;
;                     const f32x4 v0 = *(const f32x4*)(base + o2) + acc[ai][bj][m][0], v1 = *(const f32x4*)(base + o2 + 4) + acc[ai][bj][m][1];
;                     u32x4 w; w.x = pk2(v0[0], v0[1]); w.y = pk2(v0[2], v0[3]); w.z = pk2(v1[0], v1[1]); w.w = pk2(v1[2], v1[3]); *(u32x4*)(xb + o2) = w;
;                     s += ((v0[0] * v0[0] + v0[1] * v0[1]) + (v0[2] * v0[2] + v0[3] * v0[3])) + ((v1[0] * v1[0] + v1[1] * v1[1]) + (v1[2] * v1[2] + v1[3] * v1[3])); }
;                 s += __shfl_xor(s, 16); s += __shfl_xor(s, 32);
;                 if (fq == 0) atomicAdd(rowsq + row, s);
;                 if (m & 1) asm volatile("" ::: "memory"); }
.LBB0_635:
	s_lshl_b32 s15, s24, 8
	v_mov_b32_e32 v144, v148
	v_mov_b32_e32 v155, v149
	s_add_i32 s15, s15, s34
	v_readlane_b32 s48, v255, 0
	v_add_u32_e32 v146, s15, v144
	s_lshl_b32 s15, s22, 8
	s_or_b32 s15, s15, s35
	v_lshl_add_u32 v144, v155, 3, s15
	v_ashrrev_i32_e32 v147, 31, v146
	v_ashrrev_i32_e32 v145, 31, v144
	v_lshlrev_b64 v[156:157], 10, v[146:147]
	v_lshl_add_u64 v[164:165], v[156:157], 0, v[144:145]
	v_readlane_b32 s49, v255, 1
	v_lshl_add_u64 v[166:167], v[164:165], 2, s[48:49]
	global_load_dwordx4 v[156:159], v[166:167], off nt
	global_load_dwordx4 v[160:163], v[166:167], off offset:16 nt
	v_lshl_add_u64 v[164:165], v[164:165], 1, s[46:47]
	s_waitcnt vmcnt(0)
	v_pk_add_f32 v[126:127], v[126:127], v[158:159]
	v_pk_add_f32 v[168:169], v[124:125], v[156:157]
	v_pk_add_f32 v[162:163], v[122:123], v[162:163]
	v_pk_add_f32 v[160:161], v[120:121], v[160:161]
	v_cvt_pk_bf16_f32 v120, v168, v169
	v_cvt_pk_bf16_f32 v121, v126, v127
	v_cvt_pk_bf16_f32 v122, v160, v161
	v_cvt_pk_bf16_f32 v123, v162, v163
	global_store_dwordx4 v[164:165], v[120:123], off
	global_load_dwordx4 v[122:125], v[166:167], off offset:512 nt
	s_nop 0
	global_load_dwordx4 v[156:159], v[166:167], off offset:528 nt
	v_and_b32_e32 v121, 64, v154
	v_mul_f32_e32 v167, v169, v169
	v_mul_f32_e32 v127, v127, v127
	v_mul_f32_e32 v161, v161, v161
	v_mul_f32_e32 v163, v163, v163
	v_xor_b32_e32 v120, 16, v154
	v_add_u32_e32 v121, 64, v121
	v_fmac_f32_e32 v167, v168, v168
	v_fmac_f32_e32 v127, v126, v126
	v_fmac_f32_e32 v161, v160, v160
	v_fmac_f32_e32 v163, v162, v162
	v_cmp_lt_i32_e32 vcc, v120, v121
	v_add_f32_e32 v126, v167, v127
	v_add_f32_e32 v127, v161, v163
	v_cndmask_b32_e32 v120, v154, v120, vcc
	v_add_f32_e32 v126, v126, v127
	v_lshlrev_b32_e32 v120, 2, v120
	v_xor_b32_e32 v166, 32, v154
	v_cmp_lt_i32_e32 vcc, v166, v121
	s_waitcnt vmcnt(1)
	v_pk_add_f32 v[118:119], v[118:119], v[124:125]
	v_pk_add_f32 v[116:117], v[116:117], v[122:123]
	s_waitcnt vmcnt(0)
	v_pk_add_f32 v[122:123], v[114:115], v[158:159]
	v_pk_add_f32 v[124:125], v[112:113], v[156:157]
	v_mul_f32_e32 v112, v117, v117
	v_mul_f32_e32 v113, v119, v119
	v_mul_f32_e32 v114, v125, v125
	v_mul_f32_e32 v115, v123, v123
	v_fmac_f32_e32 v112, v116, v116
	v_fmac_f32_e32 v113, v118, v118
	v_fmac_f32_e32 v114, v124, v124
	v_fmac_f32_e32 v115, v122, v122
	v_add_f32_e32 v112, v112, v113
	v_add_f32_e32 v113, v114, v115
	v_add_f32_e32 v112, v112, v113
	v_add_f32_e32 v112, v126, v112
	ds_bpermute_b32 v113, v120, v112
	v_cndmask_b32_e32 v114, v154, v166, vcc
	v_lshlrev_b32_e32 v114, 2, v114
	v_cmp_eq_u32_e32 vcc, 0, v155
	v_cvt_pk_bf16_f32 v116, v116, v117
	s_waitcnt lgkmcnt(0)
	v_add_f32_e32 v112, v112, v113
	ds_bpermute_b32 v113, v114, v112
	v_cvt_pk_bf16_f32 v117, v118, v119
	v_cvt_pk_bf16_f32 v118, v124, v125
	v_cvt_pk_bf16_f32 v119, v122, v123
	global_store_dwordx4 v[164:165], v[116:119], off offset:256
	s_and_saveexec_b64 s[22:23], vcc
	s_cbranch_execz .LBB0_637
	v_lshl_add_u64 v[116:117], v[146:147], 2, s[70:71]
	s_waitcnt lgkmcnt(0)
	v_add_f32_e32 v112, v112, v113
	global_atomic_add_f32 v[116:117], v112, off
.LBB0_637:
	s_or_b64 exec, exec, s[22:23]
	v_add_u32_e32 v112, 16, v146
	s_waitcnt lgkmcnt(0)
	v_ashrrev_i32_e32 v113, 31, v112
	v_lshlrev_b64 v[116:117], 10, v[112:113]
	v_readlane_b32 s48, v255, 0
	v_lshl_add_u64 v[126:127], v[116:117], 0, v[144:145]
	v_readlane_b32 s49, v255, 1
	v_lshl_add_u64 v[156:157], v[126:127], 2, s[48:49]
	global_load_dwordx4 v[116:119], v[156:157], off nt
	global_load_dwordx4 v[122:125], v[156:157], off offset:16 nt
	v_lshl_add_u64 v[126:127], v[126:127], 1, s[46:47]
	s_waitcnt vmcnt(1)
	v_pk_add_f32 v[118:119], v[110:111], v[118:119]
	v_pk_add_f32 v[116:117], v[108:109], v[116:117]
	s_waitcnt vmcnt(0)
	v_pk_add_f32 v[124:125], v[106:107], v[124:125]
	v_pk_add_f32 v[122:123], v[104:105], v[122:123]
	v_cvt_pk_bf16_f32 v104, v116, v117
	v_cvt_pk_bf16_f32 v105, v118, v119
	v_cvt_pk_bf16_f32 v106, v122, v123
	v_cvt_pk_bf16_f32 v107, v124, v125
	global_store_dwordx4 v[126:127], v[104:107], off
	global_load_dwordx4 v[104:107], v[156:157], off offset:512 nt
	s_nop 0
	global_load_dwordx4 v[108:111], v[156:157], off offset:528 nt
	v_mul_f32_e32 v115, v117, v117
	v_mul_f32_e32 v117, v119, v119
	v_mul_f32_e32 v119, v123, v123
	v_mul_f32_e32 v121, v125, v125
	v_fmac_f32_e32 v115, v116, v116
	v_fmac_f32_e32 v117, v118, v118
	v_fmac_f32_e32 v119, v122, v122
	v_fmac_f32_e32 v121, v124, v124
	v_add_f32_e32 v115, v115, v117
	v_add_f32_e32 v116, v119, v121
	v_add_f32_e32 v115, v115, v116
	s_waitcnt vmcnt(1)
	v_pk_add_f32 v[102:103], v[102:103], v[106:107]
	v_pk_add_f32 v[100:101], v[100:101], v[104:105]
	s_waitcnt vmcnt(0)
	v_pk_add_f32 v[104:105], v[98:99], v[110:111]
	v_pk_add_f32 v[106:107], v[96:97], v[108:109]
	v_mul_f32_e32 v96, v101, v101
	v_mul_f32_e32 v97, v103, v103
	v_mul_f32_e32 v98, v107, v107
	v_mul_f32_e32 v99, v105, v105
	v_fmac_f32_e32 v96, v100, v100
	v_fmac_f32_e32 v97, v102, v102
	v_fmac_f32_e32 v98, v106, v106
	v_fmac_f32_e32 v99, v104, v104
	v_add_f32_e32 v96, v96, v97
	v_add_f32_e32 v97, v98, v99
	v_add_f32_e32 v96, v96, v97
	v_add_f32_e32 v96, v115, v96
	ds_bpermute_b32 v97, v120, v96
	v_cvt_pk_bf16_f32 v98, v100, v101
	v_cvt_pk_bf16_f32 v99, v102, v103
	v_cvt_pk_bf16_f32 v100, v106, v107
	v_cvt_pk_bf16_f32 v101, v104, v105
	s_waitcnt lgkmcnt(0)
	v_add_f32_e32 v96, v96, v97
	ds_bpermute_b32 v97, v114, v96
	global_store_dwordx4 v[126:127], v[98:101], off offset:256
	s_and_saveexec_b64 s[22:23], vcc
	s_cbranch_execz .LBB0_639
	v_lshl_add_u64 v[98:99], v[112:113], 2, s[70:71]
	s_waitcnt lgkmcnt(0)
	v_add_f32_e32 v96, v96, v97
	global_atomic_add_f32 v[98:99], v96, off
; __device__ __forceinline__ unsigned pk2(float a, float b) { f32x2_t v = {a, b}; bf16x2v_t r = __builtin_convertvector(v, bf16x2v_t); return __builtin_bit_cast(unsigned, r); }
;     __device__ __forceinline__ void operator()(const f32x4 (&acc)[2][2][4][2], const Unit& u, int wr, int wc, int fr, int fq) const {
;     ...
;             for (int m = 0; m < 4; ++m) { const int row = row0 + ai * HALF + m * 16; const size_t off = (size_t)row * ldc + col0; float s = 0.f;
; #pragma unroll
;                 for (int bj = 0; bj < 2; ++bj) { const size_t o2 = off + bj * HALF;
;                     const f32x4 v0 = *(const f32x4*)(base + o2) + acc[ai][bj][m][0], v1 = *(const f32x4*)(base + o2 + 4) + acc[ai][bj][m][1];
;                     u32x4 w; w.x = pk2(v0[0], v0[1]); w.y = pk2(v0[2], v0[3]); w.z = pk2(v1[0], v1[1]); w.w = pk2(v1[2], v1[3]); *(u32x4*)(xb + o2) = w;
;                     s += ((v0[0] * v0[0] + v0[1] * v0[1]) + (v0[2] * v0[2] + v0[3] * v0[3])) + ((v1[0] * v1[0] + v1[1] * v1[1]) + (v1[2] * v1[2] + v1[3] * v1[3])); }
;                 s += __shfl_xor(s, 16); s += __shfl_xor(s, 32);
;                 if (fq == 0) atomicAdd(rowsq + row, s);
;                 if (m & 1) asm volatile("" ::: "memory"); }
.LBB0_639:
	s_or_b64 exec, exec, s[22:23]
	v_add_u32_e32 v96, 32, v146
	s_waitcnt lgkmcnt(0)
	v_ashrrev_i32_e32 v97, 31, v96
	v_lshlrev_b64 v[98:99], 10, v[96:97]
	v_readlane_b32 s48, v255, 0
	v_lshl_add_u64 v[106:107], v[98:99], 0, v[144:145]
	v_readlane_b32 s49, v255, 1
	v_lshl_add_u64 v[108:109], v[106:107], 2, s[48:49]
	global_load_dwordx4 v[98:101], v[108:109], off nt
	global_load_dwordx4 v[102:105], v[108:109], off offset:16 nt
	v_lshl_add_u64 v[106:107], v[106:107], 1, s[46:47]
	s_waitcnt vmcnt(1)
	v_pk_add_f32 v[100:101], v[94:95], v[100:101]
	v_pk_add_f32 v[98:99], v[92:93], v[98:99]
	s_waitcnt vmcnt(0)
	v_pk_add_f32 v[104:105], v[90:91], v[104:105]
	v_pk_add_f32 v[102:103], v[88:89], v[102:103]
	v_cvt_pk_bf16_f32 v88, v98, v99
	v_cvt_pk_bf16_f32 v89, v100, v101
	v_cvt_pk_bf16_f32 v90, v102, v103
	v_cvt_pk_bf16_f32 v91, v104, v105
	global_store_dwordx4 v[106:107], v[88:91], off
	global_load_dwordx4 v[88:91], v[108:109], off offset:512 nt
	s_nop 0
	global_load_dwordx4 v[92:95], v[108:109], off offset:528 nt
	v_mul_f32_e32 v99, v99, v99
	v_mul_f32_e32 v101, v101, v101
	v_mul_f32_e32 v103, v103, v103
	v_mul_f32_e32 v105, v105, v105
	v_fmac_f32_e32 v99, v98, v98
	v_fmac_f32_e32 v101, v100, v100
	v_fmac_f32_e32 v103, v102, v102
	v_fmac_f32_e32 v105, v104, v104
	v_add_f32_e32 v98, v99, v101
	v_add_f32_e32 v99, v103, v105
	v_add_f32_e32 v98, v98, v99
	s_waitcnt vmcnt(1)
	v_pk_add_f32 v[86:87], v[86:87], v[90:91]
	v_pk_add_f32 v[84:85], v[84:85], v[88:89]
	s_waitcnt vmcnt(0)
	v_pk_add_f32 v[88:89], v[82:83], v[94:95]
	v_pk_add_f32 v[90:91], v[80:81], v[92:93]
	v_mul_f32_e32 v80, v85, v85
	v_mul_f32_e32 v81, v87, v87
	v_mul_f32_e32 v82, v91, v91
	v_mul_f32_e32 v83, v89, v89
	v_fmac_f32_e32 v80, v84, v84
	v_fmac_f32_e32 v81, v86, v86
	v_fmac_f32_e32 v82, v90, v90
	v_fmac_f32_e32 v83, v88, v88
	v_add_f32_e32 v80, v80, v81
	v_add_f32_e32 v81, v82, v83
	v_add_f32_e32 v80, v80, v81
	v_add_f32_e32 v80, v98, v80
	ds_bpermute_b32 v81, v120, v80
	v_cvt_pk_bf16_f32 v82, v84, v85
	v_cvt_pk_bf16_f32 v83, v86, v87
	v_cvt_pk_bf16_f32 v84, v90, v91
	v_cvt_pk_bf16_f32 v85, v88, v89
	s_waitcnt lgkmcnt(0)
	v_add_f32_e32 v80, v80, v81
	ds_bpermute_b32 v81, v114, v80
	global_store_dwordx4 v[106:107], v[82:85], off offset:256
	s_and_saveexec_b64 s[22:23], vcc
	s_cbranch_execz .LBB0_641
	v_lshl_add_u64 v[82:83], v[96:97], 2, s[70:71]
	s_waitcnt lgkmcnt(0)
	v_add_f32_e32 v80, v80, v81
	global_atomic_add_f32 v[82:83], v80, off
.LBB0_641:
	s_or_b64 exec, exec, s[22:23]
	v_add_u32_e32 v80, 48, v146
	s_waitcnt lgkmcnt(0)
	v_ashrrev_i32_e32 v81, 31, v80
	v_lshlrev_b64 v[82:83], 10, v[80:81]
	v_readlane_b32 s48, v255, 0
	v_lshl_add_u64 v[90:91], v[82:83], 0, v[144:145]
	v_readlane_b32 s49, v255, 1
	v_lshl_add_u64 v[92:93], v[90:91], 2, s[48:49]
	global_load_dwordx4 v[82:85], v[92:93], off nt
	global_load_dwordx4 v[86:89], v[92:93], off offset:16 nt
	v_lshl_add_u64 v[90:91], v[90:91], 1, s[46:47]
	s_waitcnt vmcnt(1)
	v_pk_add_f32 v[84:85], v[78:79], v[84:85]
	v_pk_add_f32 v[82:83], v[76:77], v[82:83]
	s_waitcnt vmcnt(0)
	v_pk_add_f32 v[88:89], v[74:75], v[88:89]
	v_pk_add_f32 v[86:87], v[72:73], v[86:87]
	v_cvt_pk_bf16_f32 v72, v82, v83
	v_cvt_pk_bf16_f32 v73, v84, v85
	v_cvt_pk_bf16_f32 v74, v86, v87
	v_cvt_pk_bf16_f32 v75, v88, v89
	global_store_dwordx4 v[90:91], v[72:75], off
	global_load_dwordx4 v[72:75], v[92:93], off offset:512 nt
	s_nop 0
	global_load_dwordx4 v[76:79], v[92:93], off offset:528 nt
	v_mul_f32_e32 v83, v83, v83
	v_mul_f32_e32 v85, v85, v85
	v_mul_f32_e32 v87, v87, v87
	v_mul_f32_e32 v89, v89, v89
	v_fmac_f32_e32 v83, v82, v82
	v_fmac_f32_e32 v85, v84, v84
	v_fmac_f32_e32 v87, v86, v86
	v_fmac_f32_e32 v89, v88, v88
	v_add_f32_e32 v82, v83, v85
	v_add_f32_e32 v83, v87, v89
	v_add_f32_e32 v82, v82, v83
	s_waitcnt vmcnt(1)
	v_pk_add_f32 v[70:71], v[70:71], v[74:75]
	v_pk_add_f32 v[68:69], v[68:69], v[72:73]
	s_waitcnt vmcnt(0)
	v_pk_add_f32 v[72:73], v[66:67], v[78:79]
	v_pk_add_f32 v[74:75], v[64:65], v[76:77]
	v_mul_f32_e32 v64, v69, v69
	v_mul_f32_e32 v65, v71, v71
	v_mul_f32_e32 v66, v75, v75
	v_mul_f32_e32 v67, v73, v73
	v_fmac_f32_e32 v64, v68, v68
	v_fmac_f32_e32 v65, v70, v70
	v_fmac_f32_e32 v66, v74, v74
	v_fmac_f32_e32 v67, v72, v72
	v_add_f32_e32 v64, v64, v65
	v_add_f32_e32 v65, v66, v67
	v_add_f32_e32 v64, v64, v65
	v_add_f32_e32 v64, v82, v64
	ds_bpermute_b32 v65, v120, v64
	v_cvt_pk_bf16_f32 v66, v68, v69
	v_cvt_pk_bf16_f32 v67, v70, v71
	v_cvt_pk_bf16_f32 v68, v74, v75
	v_cvt_pk_bf16_f32 v69, v72, v73
	s_waitcnt lgkmcnt(0)
	v_add_f32_e32 v64, v64, v65
	ds_bpermute_b32 v65, v114, v64
	global_store_dwordx4 v[90:91], v[66:69], off offset:256
	s_and_saveexec_b64 s[22:23], vcc
	s_cbranch_execz .LBB0_643
	v_lshl_add_u64 v[66:67], v[80:81], 2, s[70:71]
	s_waitcnt lgkmcnt(0)
	v_add_f32_e32 v64, v64, v65
	global_atomic_add_f32 v[66:67], v64, off
; __device__ __forceinline__ unsigned pk2(float a, float b) { f32x2_t v = {a, b}; bf16x2v_t r = __builtin_convertvector(v, bf16x2v_t); return __builtin_bit_cast(unsigned, r); }
;     __device__ __forceinline__ void operator()(const f32x4 (&acc)[2][2][4][2], const Unit& u, int wr, int wc, int fr, int fq) const {
;     ...
;             for (int m = 0; m < 4; ++m) { const int row = row0 + ai * HALF + m * 16; const size_t off = (size_t)row * ldc + col0; float s = 0.f;
; #pragma unroll
;                 for (int bj = 0; bj < 2; ++bj) { const size_t o2 = off + bj * HALF;
;                     const f32x4 v0 = *(const f32x4*)(base + o2) + acc[ai][bj][m][0], v1 = *(const f32x4*)(base + o2 + 4) + acc[ai][bj][m][1];
;                     u32x4 w; w.x = pk2(v0[0], v0[1]); w.y = pk2(v0[2], v0[3]); w.z = pk2(v1[0], v1[1]); w.w = pk2(v1[2], v1[3]); *(u32x4*)(xb + o2) = w;
;                     s += ((v0[0] * v0[0] + v0[1] * v0[1]) + (v0[2] * v0[2] + v0[3] * v0[3])) + ((v1[0] * v1[0] + v1[1] * v1[1]) + (v1[2] * v1[2] + v1[3] * v1[3])); }
;                 s += __shfl_xor(s, 16); s += __shfl_xor(s, 32);
;                 if (fq == 0) atomicAdd(rowsq + row, s);
;                 if (m & 1) asm volatile("" ::: "memory"); }
.LBB0_643:
	s_or_b64 exec, exec, s[22:23]
	v_add_u32_e32 v64, 0x80, v146
	s_waitcnt lgkmcnt(0)
	v_ashrrev_i32_e32 v65, 31, v64
	v_lshlrev_b64 v[66:67], 10, v[64:65]
	v_readlane_b32 s48, v255, 0
	v_lshl_add_u64 v[74:75], v[66:67], 0, v[144:145]
	v_readlane_b32 s49, v255, 1
	v_lshl_add_u64 v[76:77], v[74:75], 2, s[48:49]
	global_load_dwordx4 v[66:69], v[76:77], off nt
	global_load_dwordx4 v[70:73], v[76:77], off offset:16 nt
	v_lshl_add_u64 v[74:75], v[74:75], 1, s[46:47]
	s_waitcnt vmcnt(1)
	v_pk_add_f32 v[68:69], v[62:63], v[68:69]
	v_pk_add_f32 v[66:67], v[60:61], v[66:67]
	s_waitcnt vmcnt(0)
	v_pk_add_f32 v[72:73], v[58:59], v[72:73]
	v_pk_add_f32 v[70:71], v[56:57], v[70:71]
	v_cvt_pk_bf16_f32 v56, v66, v67
	v_cvt_pk_bf16_f32 v57, v68, v69
	v_cvt_pk_bf16_f32 v58, v70, v71
	v_cvt_pk_bf16_f32 v59, v72, v73
	global_store_dwordx4 v[74:75], v[56:59], off
	global_load_dwordx4 v[56:59], v[76:77], off offset:512 nt
	s_nop 0
	global_load_dwordx4 v[60:63], v[76:77], off offset:528 nt
	v_mul_f32_e32 v67, v67, v67
	v_mul_f32_e32 v69, v69, v69
	v_mul_f32_e32 v71, v71, v71
	v_mul_f32_e32 v73, v73, v73
	v_fmac_f32_e32 v67, v66, v66
	v_fmac_f32_e32 v69, v68, v68
	v_fmac_f32_e32 v71, v70, v70
	v_fmac_f32_e32 v73, v72, v72
	v_add_f32_e32 v66, v67, v69
	v_add_f32_e32 v67, v71, v73
	v_add_f32_e32 v66, v66, v67
	s_waitcnt vmcnt(1)
	v_pk_add_f32 v[54:55], v[54:55], v[58:59]
	v_pk_add_f32 v[52:53], v[52:53], v[56:57]
	s_waitcnt vmcnt(0)
	v_pk_add_f32 v[56:57], v[50:51], v[62:63]
	v_pk_add_f32 v[58:59], v[48:49], v[60:61]
	v_mul_f32_e32 v48, v53, v53
	v_mul_f32_e32 v49, v55, v55
	v_mul_f32_e32 v50, v59, v59
	v_mul_f32_e32 v51, v57, v57
	v_fmac_f32_e32 v48, v52, v52
	v_fmac_f32_e32 v49, v54, v54
	v_fmac_f32_e32 v50, v58, v58
	v_fmac_f32_e32 v51, v56, v56
	v_add_f32_e32 v48, v48, v49
	v_add_f32_e32 v49, v50, v51
	v_add_f32_e32 v48, v48, v49
	v_add_f32_e32 v48, v66, v48
	ds_bpermute_b32 v49, v120, v48
	v_cvt_pk_bf16_f32 v50, v52, v53
	v_cvt_pk_bf16_f32 v51, v54, v55
	v_cvt_pk_bf16_f32 v52, v58, v59
	v_cvt_pk_bf16_f32 v53, v56, v57
	s_waitcnt lgkmcnt(0)
	v_add_f32_e32 v48, v48, v49
	ds_bpermute_b32 v49, v114, v48
	global_store_dwordx4 v[74:75], v[50:53], off offset:256
	s_and_saveexec_b64 s[22:23], vcc
	s_cbranch_execz .LBB0_645
	v_lshl_add_u64 v[50:51], v[64:65], 2, s[70:71]
	s_waitcnt lgkmcnt(0)
	v_add_f32_e32 v48, v48, v49
	global_atomic_add_f32 v[50:51], v48, off
.LBB0_645:
	s_or_b64 exec, exec, s[22:23]
	v_add_u32_e32 v48, 0x90, v146
	s_waitcnt lgkmcnt(0)
	v_ashrrev_i32_e32 v49, 31, v48
	v_lshlrev_b64 v[50:51], 10, v[48:49]
	v_readlane_b32 s48, v255, 0
	v_lshl_add_u64 v[58:59], v[50:51], 0, v[144:145]
	v_readlane_b32 s49, v255, 1
	v_lshl_add_u64 v[60:61], v[58:59], 2, s[48:49]
	global_load_dwordx4 v[50:53], v[60:61], off nt
	global_load_dwordx4 v[54:57], v[60:61], off offset:16 nt
	v_lshl_add_u64 v[58:59], v[58:59], 1, s[46:47]
	s_waitcnt vmcnt(1)
	v_pk_add_f32 v[52:53], v[46:47], v[52:53]
	v_pk_add_f32 v[50:51], v[44:45], v[50:51]
	s_waitcnt vmcnt(0)
	v_pk_add_f32 v[56:57], v[42:43], v[56:57]
	v_pk_add_f32 v[54:55], v[40:41], v[54:55]
	v_cvt_pk_bf16_f32 v40, v50, v51
	v_cvt_pk_bf16_f32 v41, v52, v53
	v_cvt_pk_bf16_f32 v42, v54, v55
	v_cvt_pk_bf16_f32 v43, v56, v57
	global_store_dwordx4 v[58:59], v[40:43], off
	global_load_dwordx4 v[40:43], v[60:61], off offset:512 nt
	s_nop 0
	global_load_dwordx4 v[44:47], v[60:61], off offset:528 nt
	v_mul_f32_e32 v51, v51, v51
	v_mul_f32_e32 v53, v53, v53
	v_mul_f32_e32 v55, v55, v55
	v_mul_f32_e32 v57, v57, v57
	v_fmac_f32_e32 v51, v50, v50
	v_fmac_f32_e32 v53, v52, v52
	v_fmac_f32_e32 v55, v54, v54
	v_fmac_f32_e32 v57, v56, v56
	v_add_f32_e32 v50, v51, v53
	v_add_f32_e32 v51, v55, v57
	v_add_f32_e32 v50, v50, v51
	s_waitcnt vmcnt(1)
	v_pk_add_f32 v[38:39], v[38:39], v[42:43]
	v_pk_add_f32 v[36:37], v[36:37], v[40:41]
	s_waitcnt vmcnt(0)
	v_pk_add_f32 v[40:41], v[34:35], v[46:47]
	v_pk_add_f32 v[42:43], v[32:33], v[44:45]
	v_mul_f32_e32 v32, v37, v37
	v_mul_f32_e32 v33, v39, v39
	v_mul_f32_e32 v34, v43, v43
	v_mul_f32_e32 v35, v41, v41
	v_fmac_f32_e32 v32, v36, v36
	v_fmac_f32_e32 v33, v38, v38
	v_fmac_f32_e32 v34, v42, v42
	v_fmac_f32_e32 v35, v40, v40
	v_add_f32_e32 v32, v32, v33
	v_add_f32_e32 v33, v34, v35
	v_add_f32_e32 v32, v32, v33
	v_add_f32_e32 v32, v50, v32
	ds_bpermute_b32 v33, v120, v32
	v_cvt_pk_bf16_f32 v34, v36, v37
	v_cvt_pk_bf16_f32 v35, v38, v39
	v_cvt_pk_bf16_f32 v36, v42, v43
	v_cvt_pk_bf16_f32 v37, v40, v41
	s_waitcnt lgkmcnt(0)
	v_add_f32_e32 v32, v32, v33
	ds_bpermute_b32 v33, v114, v32
	global_store_dwordx4 v[58:59], v[34:37], off offset:256
	s_and_saveexec_b64 s[22:23], vcc
	s_cbranch_execz .LBB0_647
	v_lshl_add_u64 v[34:35], v[48:49], 2, s[70:71]
	s_waitcnt lgkmcnt(0)
	v_add_f32_e32 v32, v32, v33
	global_atomic_add_f32 v[34:35], v32, off
; __device__ __forceinline__ unsigned pk2(float a, float b) { f32x2_t v = {a, b}; bf16x2v_t r = __builtin_convertvector(v, bf16x2v_t); return __builtin_bit_cast(unsigned, r); }
;     __device__ __forceinline__ void operator()(const f32x4 (&acc)[2][2][4][2], const Unit& u, int wr, int wc, int fr, int fq) const {
;     ...
;             for (int m = 0; m < 4; ++m) { const int row = row0 + ai * HALF + m * 16; const size_t off = (size_t)row * ldc + col0; float s = 0.f;
; #pragma unroll
;                 for (int bj = 0; bj < 2; ++bj) { const size_t o2 = off + bj * HALF;
;                     const f32x4 v0 = *(const f32x4*)(base + o2) + acc[ai][bj][m][0], v1 = *(const f32x4*)(base + o2 + 4) + acc[ai][bj][m][1];
;                     u32x4 w; w.x = pk2(v0[0], v0[1]); w.y = pk2(v0[2], v0[3]); w.z = pk2(v1[0], v1[1]); w.w = pk2(v1[2], v1[3]); *(u32x4*)(xb + o2) = w;
;                     s += ((v0[0] * v0[0] + v0[1] * v0[1]) + (v0[2] * v0[2] + v0[3] * v0[3])) + ((v1[0] * v1[0] + v1[1] * v1[1]) + (v1[2] * v1[2] + v1[3] * v1[3])); }
;                 s += __shfl_xor(s, 16); s += __shfl_xor(s, 32);
;                 if (fq == 0) atomicAdd(rowsq + row, s);
;                 if (m & 1) asm volatile("" ::: "memory"); }
.LBB0_647:
	s_or_b64 exec, exec, s[22:23]
	v_add_u32_e32 v32, 0xa0, v146
	s_waitcnt lgkmcnt(0)
	v_ashrrev_i32_e32 v33, 31, v32
	v_lshlrev_b64 v[34:35], 10, v[32:33]
	v_readlane_b32 s48, v255, 0
	v_lshl_add_u64 v[42:43], v[34:35], 0, v[144:145]
	v_readlane_b32 s49, v255, 1
	v_lshl_add_u64 v[44:45], v[42:43], 2, s[48:49]
	global_load_dwordx4 v[34:37], v[44:45], off nt
	global_load_dwordx4 v[38:41], v[44:45], off offset:16 nt
	v_lshl_add_u64 v[42:43], v[42:43], 1, s[46:47]
	s_waitcnt vmcnt(1)
	v_pk_add_f32 v[36:37], v[30:31], v[36:37]
	v_pk_add_f32 v[34:35], v[28:29], v[34:35]
	s_waitcnt vmcnt(0)
	v_pk_add_f32 v[40:41], v[26:27], v[40:41]
	v_pk_add_f32 v[38:39], v[24:25], v[38:39]
	v_cvt_pk_bf16_f32 v24, v34, v35
	v_cvt_pk_bf16_f32 v25, v36, v37
	v_cvt_pk_bf16_f32 v26, v38, v39
	v_cvt_pk_bf16_f32 v27, v40, v41
	global_store_dwordx4 v[42:43], v[24:27], off
	global_load_dwordx4 v[24:27], v[44:45], off offset:512 nt
	s_nop 0
	global_load_dwordx4 v[28:31], v[44:45], off offset:528 nt
	v_mul_f32_e32 v35, v35, v35
	v_mul_f32_e32 v37, v37, v37
	v_mul_f32_e32 v39, v39, v39
	v_mul_f32_e32 v41, v41, v41
	v_fmac_f32_e32 v35, v34, v34
	v_fmac_f32_e32 v37, v36, v36
	v_fmac_f32_e32 v39, v38, v38
	v_fmac_f32_e32 v41, v40, v40
	v_add_f32_e32 v34, v35, v37
	v_add_f32_e32 v35, v39, v41
	v_add_f32_e32 v34, v34, v35
	s_waitcnt vmcnt(1)
	v_pk_add_f32 v[22:23], v[22:23], v[26:27]
	v_pk_add_f32 v[20:21], v[20:21], v[24:25]
	s_waitcnt vmcnt(0)
	v_pk_add_f32 v[24:25], v[18:19], v[30:31]
	v_pk_add_f32 v[26:27], v[16:17], v[28:29]
	v_mul_f32_e32 v16, v21, v21
	v_mul_f32_e32 v17, v23, v23
	v_mul_f32_e32 v18, v27, v27
	v_mul_f32_e32 v19, v25, v25
	v_fmac_f32_e32 v16, v20, v20
	v_fmac_f32_e32 v17, v22, v22
	v_fmac_f32_e32 v18, v26, v26
	v_fmac_f32_e32 v19, v24, v24
	v_add_f32_e32 v16, v16, v17
	v_add_f32_e32 v17, v18, v19
	v_add_f32_e32 v16, v16, v17
	v_add_f32_e32 v16, v34, v16
	ds_bpermute_b32 v17, v120, v16
	v_cvt_pk_bf16_f32 v18, v20, v21
	v_cvt_pk_bf16_f32 v19, v22, v23
	v_cvt_pk_bf16_f32 v20, v26, v27
	v_cvt_pk_bf16_f32 v21, v24, v25
	s_waitcnt lgkmcnt(0)
	v_add_f32_e32 v16, v16, v17
	ds_bpermute_b32 v17, v114, v16
	global_store_dwordx4 v[42:43], v[18:21], off offset:256
	s_and_saveexec_b64 s[22:23], vcc
	s_cbranch_execz .LBB0_649
	v_lshl_add_u64 v[18:19], v[32:33], 2, s[70:71]
	s_waitcnt lgkmcnt(0)
	v_add_f32_e32 v16, v16, v17
	global_atomic_add_f32 v[18:19], v16, off
.LBB0_649:
	s_or_b64 exec, exec, s[22:23]
	v_add_u32_e32 v16, 0xb0, v146
	s_waitcnt lgkmcnt(0)
	v_ashrrev_i32_e32 v17, 31, v16
	v_lshlrev_b64 v[18:19], 10, v[16:17]
	v_readlane_b32 s48, v255, 0
	v_lshl_add_u64 v[26:27], v[18:19], 0, v[144:145]
	v_readlane_b32 s49, v255, 1
	v_lshl_add_u64 v[28:29], v[26:27], 2, s[48:49]
	global_load_dwordx4 v[18:21], v[28:29], off nt
	global_load_dwordx4 v[22:25], v[28:29], off offset:16 nt
	v_lshl_add_u64 v[26:27], v[26:27], 1, s[46:47]
	s_waitcnt vmcnt(1)
	v_pk_add_f32 v[20:21], v[14:15], v[20:21]
	v_pk_add_f32 v[18:19], v[12:13], v[18:19]
	s_waitcnt vmcnt(0)
	v_pk_add_f32 v[24:25], v[10:11], v[24:25]
	v_pk_add_f32 v[22:23], v[8:9], v[22:23]
	v_cvt_pk_bf16_f32 v8, v18, v19
	v_cvt_pk_bf16_f32 v9, v20, v21
	v_cvt_pk_bf16_f32 v10, v22, v23
	v_cvt_pk_bf16_f32 v11, v24, v25
	global_store_dwordx4 v[26:27], v[8:11], off
	global_load_dwordx4 v[8:11], v[28:29], off offset:512 nt
	s_nop 0
	global_load_dwordx4 v[12:15], v[28:29], off offset:528 nt
	v_mul_f32_e32 v19, v19, v19
	v_mul_f32_e32 v21, v21, v21
	v_mul_f32_e32 v23, v23, v23
	v_mul_f32_e32 v25, v25, v25
	v_fmac_f32_e32 v19, v18, v18
	v_fmac_f32_e32 v21, v20, v20
	v_fmac_f32_e32 v23, v22, v22
	v_fmac_f32_e32 v25, v24, v24
	v_add_f32_e32 v18, v19, v21
	v_add_f32_e32 v19, v23, v25
	v_add_f32_e32 v18, v18, v19
	s_waitcnt vmcnt(1)
	v_pk_add_f32 v[6:7], v[6:7], v[10:11]
	v_pk_add_f32 v[4:5], v[4:5], v[8:9]
	s_waitcnt vmcnt(0)
	v_pk_add_f32 v[8:9], v[2:3], v[14:15]
	v_pk_add_f32 v[10:11], v[0:1], v[12:13]
	v_mul_f32_e32 v0, v5, v5
	v_mul_f32_e32 v1, v7, v7
	v_mul_f32_e32 v2, v11, v11
	v_mul_f32_e32 v3, v9, v9
	v_fmac_f32_e32 v0, v4, v4
	v_fmac_f32_e32 v1, v6, v6
	v_fmac_f32_e32 v2, v10, v10
	v_fmac_f32_e32 v3, v8, v8
	v_add_f32_e32 v0, v0, v1
	v_add_f32_e32 v1, v2, v3
	v_add_f32_e32 v0, v0, v1
	v_add_f32_e32 v0, v18, v0
	ds_bpermute_b32 v1, v120, v0
	v_cvt_pk_bf16_f32 v2, v4, v5
	v_cvt_pk_bf16_f32 v3, v6, v7
	v_cvt_pk_bf16_f32 v4, v10, v11
	v_cvt_pk_bf16_f32 v5, v8, v9
	s_waitcnt lgkmcnt(0)
	v_add_f32_e32 v0, v0, v1
	ds_bpermute_b32 v1, v114, v0
	global_store_dwordx4 v[26:27], v[2:5], off offset:256
	s_and_saveexec_b64 s[22:23], vcc
	s_cbranch_execz .LBB0_651
	v_lshl_add_u64 v[2:3], v[16:17], 2, s[70:71]
	s_waitcnt lgkmcnt(0)
	v_add_f32_e32 v0, v0, v1
	global_atomic_add_f32 v[2:3], v0, off
